# v35 + prologue NSA-in-projection weight copy: the 8 gain-pair loads of an item issued together (one wait instead of eight)
# baseline (speedup 1.0000x reference)
.LBB0_484:
	s_or_b64 exec, exec, s[8:9]
	v_ashrrev_i32_e32 v71, 31, v70
	v_lshl_add_u64 v[120:121], v[70:71], 2, s[0:1]
	global_load_dwordx2 v[104:105], v[120:121], off
	v_ashrrev_i32_e32 v75, 31, v74
	v_lshl_add_u64 v[120:121], v[74:75], 2, s[0:1]
	global_load_dwordx2 v[106:107], v[120:121], off
	v_ashrrev_i32_e32 v77, 31, v76
	v_lshl_add_u64 v[120:121], v[76:77], 2, s[0:1]
	global_load_dwordx2 v[108:109], v[120:121], off
	v_ashrrev_i32_e32 v79, 31, v78
	v_lshl_add_u64 v[120:121], v[78:79], 2, s[0:1]
	global_load_dwordx2 v[110:111], v[120:121], off
	v_ashrrev_i32_e32 v81, 31, v80
	v_lshl_add_u64 v[120:121], v[80:81], 2, s[0:1]
	global_load_dwordx2 v[112:113], v[120:121], off
	v_ashrrev_i32_e32 v83, 31, v82
	v_lshl_add_u64 v[120:121], v[82:83], 2, s[0:1]
	global_load_dwordx2 v[114:115], v[120:121], off
	v_ashrrev_i32_e32 v85, 31, v84
	v_lshl_add_u64 v[120:121], v[84:85], 2, s[0:1]
	global_load_dwordx2 v[116:117], v[120:121], off
	v_ashrrev_i32_e32 v87, 31, v86
	v_lshl_add_u64 v[120:121], v[86:87], 2, s[0:1]
	global_load_dwordx2 v[118:119], v[120:121], off
	s_ashr_i32 s7, s6, 31
	s_waitcnt vmcnt(0)
	v_mul_f32_e32 v122, v10, v104
	v_mul_f32_e32 v123, v26, v105
	v_cvt_pk_bf16_f32 v124, v122, v123
	ds_write_b32 v102, v124
	v_mul_f32_e32 v122, v11, v104
	v_mul_f32_e32 v123, v27, v105
	v_cvt_pk_bf16_f32 v124, v122, v123
	ds_write_b32 v102, v124 offset:4
	v_mul_f32_e32 v122, v12, v104
	v_mul_f32_e32 v123, v28, v105
	v_cvt_pk_bf16_f32 v124, v122, v123
	ds_write_b32 v102, v124 offset:8
	v_mul_f32_e32 v122, v13, v104
	v_mul_f32_e32 v123, v29, v105
	v_cvt_pk_bf16_f32 v124, v122, v123
	ds_write_b32 v102, v124 offset:12
	v_mul_f32_e32 v122, v2, v106
	v_mul_f32_e32 v123, v34, v107
	v_cvt_pk_bf16_f32 v124, v122, v123
	ds_write_b32 v102, v124 offset:1040
	v_mul_f32_e32 v122, v3, v106
	v_mul_f32_e32 v123, v35, v107
	v_cvt_pk_bf16_f32 v124, v122, v123
	ds_write_b32 v102, v124 offset:1044
	v_mul_f32_e32 v122, v4, v106
	v_mul_f32_e32 v123, v36, v107
	v_cvt_pk_bf16_f32 v124, v122, v123
	ds_write_b32 v102, v124 offset:1048
	v_mul_f32_e32 v122, v5, v106
	v_mul_f32_e32 v123, v37, v107
	v_cvt_pk_bf16_f32 v124, v122, v123
	ds_write_b32 v102, v124 offset:1052
	v_mul_f32_e32 v122, v6, v108
	v_mul_f32_e32 v123, v42, v109
	v_cvt_pk_bf16_f32 v124, v122, v123
	ds_write_b32 v102, v124 offset:2080
	v_mul_f32_e32 v122, v7, v108
	v_mul_f32_e32 v123, v43, v109
	v_cvt_pk_bf16_f32 v124, v122, v123
	ds_write_b32 v102, v124 offset:2084
	v_mul_f32_e32 v122, v8, v108
	v_mul_f32_e32 v123, v44, v109
	v_cvt_pk_bf16_f32 v124, v122, v123
	ds_write_b32 v102, v124 offset:2088
	v_mul_f32_e32 v122, v9, v108
	v_mul_f32_e32 v123, v45, v109
	v_cvt_pk_bf16_f32 v124, v122, v123
	ds_write_b32 v102, v124 offset:2092
	v_mul_f32_e32 v122, v14, v110
	v_mul_f32_e32 v123, v46, v111
	v_cvt_pk_bf16_f32 v124, v122, v123
	ds_write_b32 v102, v124 offset:3120
	v_mul_f32_e32 v122, v15, v110
	v_mul_f32_e32 v123, v47, v111
	v_cvt_pk_bf16_f32 v124, v122, v123
	ds_write_b32 v102, v124 offset:3124
	v_mul_f32_e32 v122, v16, v110
	v_mul_f32_e32 v123, v48, v111
	v_cvt_pk_bf16_f32 v124, v122, v123
	ds_write_b32 v102, v124 offset:3128
	v_mul_f32_e32 v122, v17, v110
	v_mul_f32_e32 v123, v49, v111
	v_cvt_pk_bf16_f32 v124, v122, v123
	ds_write_b32 v102, v124 offset:3132
	v_mul_f32_e32 v122, v18, v112
	v_mul_f32_e32 v123, v50, v113
	v_cvt_pk_bf16_f32 v124, v122, v123
	ds_write_b32 v102, v124 offset:4160
	v_mul_f32_e32 v122, v19, v112
	v_mul_f32_e32 v123, v51, v113
	v_cvt_pk_bf16_f32 v124, v122, v123
	ds_write_b32 v102, v124 offset:4164
	v_mul_f32_e32 v122, v20, v112
	v_mul_f32_e32 v123, v52, v113
	v_cvt_pk_bf16_f32 v124, v122, v123
	ds_write_b32 v102, v124 offset:4168
	v_mul_f32_e32 v122, v21, v112
	v_mul_f32_e32 v123, v53, v113
	v_cvt_pk_bf16_f32 v124, v122, v123
	ds_write_b32 v102, v124 offset:4172
	v_mul_f32_e32 v122, v22, v114
	v_mul_f32_e32 v123, v54, v115
	v_cvt_pk_bf16_f32 v124, v122, v123
	ds_write_b32 v102, v124 offset:5200
	v_mul_f32_e32 v122, v23, v114
	v_mul_f32_e32 v123, v55, v115
	v_cvt_pk_bf16_f32 v124, v122, v123
	ds_write_b32 v102, v124 offset:5204
	v_mul_f32_e32 v122, v24, v114
	v_mul_f32_e32 v123, v56, v115
	v_cvt_pk_bf16_f32 v124, v122, v123
	ds_write_b32 v102, v124 offset:5208
	v_mul_f32_e32 v122, v25, v114
	v_mul_f32_e32 v123, v57, v115
	v_cvt_pk_bf16_f32 v124, v122, v123
	ds_write_b32 v102, v124 offset:5212
	v_mul_f32_e32 v122, v30, v116
	v_mul_f32_e32 v123, v58, v117
	v_cvt_pk_bf16_f32 v124, v122, v123
	ds_write_b32 v102, v124 offset:6240
	v_mul_f32_e32 v122, v31, v116
	v_mul_f32_e32 v123, v59, v117
	v_cvt_pk_bf16_f32 v124, v122, v123
	ds_write_b32 v102, v124 offset:6244
	v_mul_f32_e32 v122, v32, v116
	v_mul_f32_e32 v123, v60, v117
	v_cvt_pk_bf16_f32 v124, v122, v123
	ds_write_b32 v102, v124 offset:6248
	v_mul_f32_e32 v122, v33, v116
	v_mul_f32_e32 v123, v61, v117
	v_cvt_pk_bf16_f32 v124, v122, v123
	ds_write_b32 v102, v124 offset:6252
	v_mul_f32_e32 v122, v38, v118
	v_mul_f32_e32 v123, v62, v119
	v_cvt_pk_bf16_f32 v124, v122, v123
	ds_write_b32 v102, v124 offset:7280
	v_mul_f32_e32 v122, v39, v118
	v_mul_f32_e32 v123, v63, v119
	v_cvt_pk_bf16_f32 v124, v122, v123
	ds_write_b32 v102, v124 offset:7284
	v_mul_f32_e32 v122, v40, v118
	v_mul_f32_e32 v123, v64, v119
	v_cvt_pk_bf16_f32 v124, v122, v123
	ds_write_b32 v102, v124 offset:7288
	v_mul_f32_e32 v122, v41, v118
	v_mul_f32_e32 v123, v65, v119
	v_cvt_pk_bf16_f32 v124, v122, v123
	ds_write_b32 v102, v124 offset:7292
	s_waitcnt lgkmcnt(0)
	v_add_u32_e32 v6, s14, v103
	v_add_u32_e32 v4, 0xffea8000, v6
	v_lshl_add_u64 v[2:3], s[6:7], 1, v[68:69]
	v_cmp_gt_i32_e32 vcc, s12, v4
	s_and_saveexec_b64 s[6:7], vcc
	s_cbranch_execz .LBB0_486
	ds_read2_b32 v[8:9], v100 offset1:65
	ds_read2_b32 v[10:11], v100 offset0:130 offset1:195
	v_ashrrev_i32_e32 v5, 31, v4
	v_lshlrev_b64 v[4:5], 13, v[4:5]
	v_lshl_add_u64 v[4:5], v[2:3], 0, v[4:5]
	s_waitcnt lgkmcnt(0)
	global_store_dwordx4 v[4:5], v[8:11], off
